# P3 out-proj: first unit's residual tile x is loaded into the accumulators before the P2->P3 grid barrier (MFMA C-init), its epilogue becomes store-only; plus B-mixer mask dispatch
# speedup vs baseline: 1.0025x; 1.0025x over previous
;     __device__ __forceinline__ void operator()(const f32x4 (&acc)[2][2][4][2], const Unit& u, int wr, int wc, int fr, int fq) const {
;         const int row0 = u.pm * BM + wr * 64 + fr, col0 = u.pn * BM + wc * 32 + 4 * fq;
; #pragma unroll
;         for (int ai = 0; ai < 2; ++ai) {
;             f32x4 res[4][2][2];
; #pragma unroll
;             for (int m = 0; m < 4; ++m) { const size_t off = (size_t)(row0 + ai * HALF + m * 16) * ldc + col0;
; #pragma unroll
;                 for (int bj = 0; bj < 2; ++bj)
; #pragma unroll
;                     for (int n = 0; n < 2; ++n) res[m][bj][n] = *(const f32x4*)(base + off + bj * HALF + n * 16); }
; __device__ __forceinline__ void grid_bar(unsigned* ctr, unsigned target) {
;     asm volatile("s_waitcnt vmcnt(0)" ::: "memory");
;     __syncthreads();
;     if (threadIdx.x == 0) {
;         __builtin_amdgcn_fence(__ATOMIC_RELEASE, "agent");
;         asm volatile("s_waitcnt vmcnt(0)" ::: "memory");
;         __hip_atomic_fetch_add(ctr, 1u, __ATOMIC_RELAXED, __HIP_MEMORY_SCOPE_AGENT);
;         while (__hip_atomic_load(ctr, __ATOMIC_RELAXED, __HIP_MEMORY_SCOPE_AGENT) < target) __builtin_amdgcn_s_sleep(2);
;         __builtin_amdgcn_fence(__ATOMIC_ACQUIRE, "agent");
;         asm volatile("s_waitcnt vmcnt(0)" ::: "memory");
;     }
;     __syncthreads();
; }
.LBB0_436:
	s_mov_b32 s101, 0
	s_cmp_gt_i32 s79, 3
	v_readlane_b32 s2, v254, 50
	s_cselect_b64 s[0:1], -1, 0
	v_readlane_b32 s3, v254, 51
	s_and_b64 s[2:3], s[2:3], s[0:1]
	s_andn2_b64 vcc, exec, s[2:3]
	s_cbranch_vccnz .LBB0_444
	s_mov_b32 s101, 0
	s_cmpk_gt_i32 s82, 0x1ff
	s_cbranch_scc1 .Lp3_nopre
	s_mov_b32 s101, 1
	v_readlane_b32 s84, v254, 0
	v_readlane_b32 s85, v254, 1
	s_and_b32 s86, s82, 7
	s_lshl_b32 s86, s86, 3
	s_bfe_u32 s87, s82, 0x30003
	s_or_b32 s86, s86, s87
	s_lshr_b32 s87, s82, 6
	v_lshrrev_b32_e32 v250, 8, v229
	v_lshlrev_b32_e32 v250, 6, v250
	v_and_b32_e32 v251, 15, v229
	v_or_b32_e32 v250, v250, v251
	v_lshl_add_u32 v250, s86, 8, v250
	v_bfe_u32 v251, v229, 6, 2
	v_lshlrev_b32_e32 v251, 5, v251
	v_bfe_u32 v252, v229, 4, 2
	v_lshl_or_b32 v251, v252, 2, v251
	v_lshl_add_u32 v251, s87, 8, v251
	v_lshlrev_b32_e32 v250, 13, v250
	v_lshl_add_u32 v250, v251, 2, v250
	global_load_dwordx4 v[124:127], v250, s[84:85]
	global_load_dwordx4 v[120:123], v250, s[84:85] offset:64
	global_load_dwordx4 v[104:107], v250, s[84:85] offset:512
	global_load_dwordx4 v[96:99], v250, s[84:85] offset:576
	s_add_u32 s88, s84, 0x20000
	s_addc_u32 s89, s85, 0
	s_nop 0
	global_load_dwordx4 v[116:119], v250, s[88:89]
	global_load_dwordx4 v[112:115], v250, s[88:89] offset:64
	global_load_dwordx4 v[88:91], v250, s[88:89] offset:512
	global_load_dwordx4 v[84:87], v250, s[88:89] offset:576
	s_add_u32 s90, s84, 0x40000
	s_addc_u32 s91, s85, 0
	s_nop 0
	global_load_dwordx4 v[108:111], v250, s[90:91]
	global_load_dwordx4 v[100:103], v250, s[90:91] offset:64
	global_load_dwordx4 v[76:79], v250, s[90:91] offset:512
	global_load_dwordx4 v[72:75], v250, s[90:91] offset:576
	s_add_u32 s92, s84, 0x60000
	s_addc_u32 s93, s85, 0
	s_nop 0
	global_load_dwordx4 v[92:95], v250, s[92:93]
	global_load_dwordx4 v[80:83], v250, s[92:93] offset:64
	global_load_dwordx4 v[68:71], v250, s[92:93] offset:512
	global_load_dwordx4 v[64:67], v250, s[92:93] offset:576
	s_add_u32 s94, s84, 0x100000
	s_addc_u32 s95, s85, 0
	s_nop 0
	global_load_dwordx4 v[60:63], v250, s[94:95]
	global_load_dwordx4 v[56:59], v250, s[94:95] offset:64
	global_load_dwordx4 v[40:43], v250, s[94:95] offset:512
	global_load_dwordx4 v[32:35], v250, s[94:95] offset:576
	s_add_u32 s96, s84, 0x120000
	s_addc_u32 s97, s85, 0
	s_nop 0
	global_load_dwordx4 v[52:55], v250, s[96:97]
	global_load_dwordx4 v[48:51], v250, s[96:97] offset:64
	global_load_dwordx4 v[24:27], v250, s[96:97] offset:512
	global_load_dwordx4 v[20:23], v250, s[96:97] offset:576
	s_add_u32 s98, s84, 0x140000
	s_addc_u32 s99, s85, 0
	s_nop 0
	global_load_dwordx4 v[44:47], v250, s[98:99]
	global_load_dwordx4 v[36:39], v250, s[98:99] offset:64
	global_load_dwordx4 v[12:15], v250, s[98:99] offset:512
	global_load_dwordx4 v[236:239], v250, s[98:99] offset:576
	s_add_u32 s88, s84, 0x160000
	s_addc_u32 s89, s85, 0
	s_nop 0
	global_load_dwordx4 v[28:31], v250, s[88:89]
	global_load_dwordx4 v[16:19], v250, s[88:89] offset:64
	global_load_dwordx4 v[240:243], v250, s[88:89] offset:512
	global_load_dwordx4 v[244:247], v250, s[88:89] offset:576
.Lp3_nopre:
	s_waitcnt vmcnt(0)
	v_cmp_eq_u32_e32 vcc, 0, v229
	s_waitcnt vmcnt(0)
	s_barrier
	s_and_saveexec_b64 s[2:3], vcc
	s_cbranch_execz .LBB0_443
	s_mov_b64 s[4:5], exec
	buffer_wbl2 sc1
	s_waitcnt vmcnt(0)
	v_mbcnt_lo_u32_b32 v0, s4, 0
	v_mbcnt_hi_u32_b32 v0, s5, v0
	v_cmp_eq_u32_e32 vcc, 0, v0
	s_and_saveexec_b64 s[6:7], vcc
	s_cbranch_execz .LBB0_440
	s_bcnt1_i32_b64 s4, s[4:5]
	v_mov_b32_e32 v0, 0
	v_mov_b32_e32 v1, s4
	global_atomic_add v0, v1, s[76:77] offset:256

;     __host__ __device__ bool next(int i, Unit& u) const { if (lo + i >= hi) return false; return base.next(lo + i, u); }
; template <class Epi, class Sched, bool ALIGN_EPI = false, bool SP2 = false>
; __device__ __forceinline__ void gemm_phase(PG8_LAS unsigned char* lds, const Gemm g, const Sched& S, const Epi& E) {
;     ...
;     for (;;) {
;         const bool has_next = S.next(ui + 1, nxt);
;         const char* nA = has_next ? (const char*)g.A + (size_t)nxt.pm * tstep : cA; const char* nB = has_next ? (const char*)g.Bt + (size_t)nxt.pn * tstep : cB;
;     ...
; #pragma unroll
;         for (int a = 0; a < 2; ++a)
; #pragma unroll
;             for (int b = 0; b < 2; ++b)
; #pragma unroll
;                 for (int m = 0; m < 4; ++m)
; #pragma unroll
;                     for (int n = 0; n < 2; ++n) acc[a][b][m][n] = (f32x4){0.f, 0.f, 0.f, 0.f};
;         cur = nxt; cA = nA; cB = nB; ++ui;
.LBB0_457:
	s_ashr_i32 s19, s18, 31
	s_lshl_b64 s[20:21], s[18:19], 20
	s_add_u32 s20, s80, s20
	s_addc_u32 s21, s81, s21
	s_and_b64 s[22:23], s[0:1], exec
	s_cselect_b32 s19, s21, s27
	s_cselect_b32 s31, s20, s26
	s_ashr_i32 s17, s16, 31
	s_lshl_b64 s[22:23], s[16:17], 20
	s_add_u32 s22, s72, s22
	s_addc_u32 s23, s73, s23
	s_and_b64 s[34:35], s[0:1], exec
	s_cselect_b32 s17, s23, s29
	s_cselect_b32 s46, s22, s28
	s_add_u32 s26, s26, 0x80080
	s_addc_u32 s27, s27, 0
	s_add_u32 s47, s28, 0x100
	s_addc_u32 s48, s29, 0
	s_mov_b32 s49, -2
	s_cmp_eq_u32 s101, 1
	s_cbranch_scc1 .Lp3_preloaded
	v_mov_b32_e32 v0, 0
	v_mov_b32_e32 v1, v0
	v_mov_b32_e32 v2, v0
	v_mov_b32_e32 v3, v0
	v_mov_b32_e32 v4, v0
	v_mov_b32_e32 v5, v0
	v_mov_b32_e32 v6, v0
	v_mov_b32_e32 v7, v0
	v_mov_b32_e32 v8, v0
	v_mov_b32_e32 v9, v0
	v_mov_b32_e32 v10, v0
	v_mov_b32_e32 v11, v0
	v_mov_b32_e32 v12, v0
	v_mov_b32_e32 v13, v0
	v_mov_b32_e32 v14, v0
	v_mov_b32_e32 v15, v0
	v_mov_b32_e32 v20, v0
	v_mov_b32_e32 v21, v0
	v_mov_b32_e32 v22, v0
	v_mov_b32_e32 v23, v0
	v_mov_b32_e32 v24, v0
	v_mov_b32_e32 v25, v0
	v_mov_b32_e32 v26, v0
	v_mov_b32_e32 v27, v0
	v_mov_b32_e32 v32, v0
	v_mov_b32_e32 v33, v0
	v_mov_b32_e32 v34, v0
	v_mov_b32_e32 v35, v0
	v_mov_b32_e32 v40, v0
	v_mov_b32_e32 v41, v0
	v_mov_b32_e32 v42, v0
	v_mov_b32_e32 v43, v0
	v_mov_b32_e32 v16, v0
	v_mov_b32_e32 v17, v0
	v_mov_b32_e32 v18, v0
	v_mov_b32_e32 v19, v0
	v_mov_b32_e32 v28, v0
	v_mov_b32_e32 v29, v0
	v_mov_b32_e32 v30, v0
	v_mov_b32_e32 v31, v0
	v_mov_b32_e32 v36, v0
	v_mov_b32_e32 v37, v0
	v_mov_b32_e32 v38, v0
	v_mov_b32_e32 v39, v0
	v_mov_b32_e32 v44, v0
	v_mov_b32_e32 v45, v0
	v_mov_b32_e32 v46, v0
	v_mov_b32_e32 v47, v0
	v_mov_b32_e32 v48, v0
	v_mov_b32_e32 v49, v0
	v_mov_b32_e32 v50, v0
	v_mov_b32_e32 v51, v0
	v_mov_b32_e32 v52, v0
	v_mov_b32_e32 v53, v0
	v_mov_b32_e32 v54, v0
	v_mov_b32_e32 v55, v0
	v_mov_b32_e32 v56, v0
	v_mov_b32_e32 v57, v0
	v_mov_b32_e32 v58, v0
	v_mov_b32_e32 v59, v0
	v_mov_b32_e32 v60, v0
	v_mov_b32_e32 v61, v0
	v_mov_b32_e32 v62, v0
	v_mov_b32_e32 v63, v0
	v_mov_b32_e32 v64, v0
	v_mov_b32_e32 v65, v0
	v_mov_b32_e32 v66, v0
	v_mov_b32_e32 v67, v0
	v_mov_b32_e32 v68, v0
	v_mov_b32_e32 v69, v0
	v_mov_b32_e32 v70, v0
	v_mov_b32_e32 v71, v0
	v_mov_b32_e32 v72, v0
	v_mov_b32_e32 v73, v0
	v_mov_b32_e32 v74, v0
	v_mov_b32_e32 v75, v0
	v_mov_b32_e32 v76, v0
	v_mov_b32_e32 v77, v0
	v_mov_b32_e32 v78, v0
	v_mov_b32_e32 v79, v0
	v_mov_b32_e32 v84, v0
	v_mov_b32_e32 v85, v0
	v_mov_b32_e32 v86, v0
	v_mov_b32_e32 v87, v0
	v_mov_b32_e32 v88, v0
	v_mov_b32_e32 v89, v0
	v_mov_b32_e32 v90, v0
	v_mov_b32_e32 v91, v0
	v_mov_b32_e32 v96, v0
	v_mov_b32_e32 v97, v0
	v_mov_b32_e32 v98, v0
	v_mov_b32_e32 v99, v0
	v_mov_b32_e32 v104, v0
	v_mov_b32_e32 v105, v0
	v_mov_b32_e32 v106, v0
	v_mov_b32_e32 v107, v0
	v_mov_b32_e32 v80, v0
	v_mov_b32_e32 v81, v0
	v_mov_b32_e32 v82, v0
	v_mov_b32_e32 v83, v0
	v_mov_b32_e32 v92, v0
	v_mov_b32_e32 v93, v0
	v_mov_b32_e32 v94, v0
	v_mov_b32_e32 v95, v0
	v_mov_b32_e32 v100, v0
	v_mov_b32_e32 v101, v0
	v_mov_b32_e32 v102, v0
	v_mov_b32_e32 v103, v0
	v_mov_b32_e32 v108, v0
	v_mov_b32_e32 v109, v0
	v_mov_b32_e32 v110, v0
	v_mov_b32_e32 v111, v0
	v_mov_b32_e32 v112, v0
	v_mov_b32_e32 v113, v0
	v_mov_b32_e32 v114, v0
	v_mov_b32_e32 v115, v0
	v_mov_b32_e32 v116, v0
	v_mov_b32_e32 v117, v0
	v_mov_b32_e32 v118, v0
	v_mov_b32_e32 v119, v0
	v_mov_b32_e32 v120, v0
	v_mov_b32_e32 v121, v0
	v_mov_b32_e32 v122, v0
	v_mov_b32_e32 v123, v0
	v_mov_b32_e32 v124, v0
	v_mov_b32_e32 v125, v0
	v_mov_b32_e32 v126, v0
	v_mov_b32_e32 v127, v0

;     __device__ __forceinline__ void operator()(const f32x4 (&acc)[2][2][4][2], const Unit& u, int wr, int wc, int fr, int fq) const {
;         const int row0 = u.pm * BM + wr * 64 + fr, col0 = u.pn * BM + wc * 32 + 4 * fq;
; #pragma unroll
;         for (int ai = 0; ai < 2; ++ai) {
;             f32x4 res[4][2][2];
; #pragma unroll
;             for (int m = 0; m < 4; ++m) { const size_t off = (size_t)(row0 + ai * HALF + m * 16) * ldc + col0;
; #pragma unroll
;                 for (int bj = 0; bj < 2; ++bj)
; #pragma unroll
;                     for (int n = 0; n < 2; ++n) res[m][bj][n] = *(const f32x4*)(base + off + bj * HALF + n * 16); }
;             asm volatile("" ::: "memory");
; #pragma unroll
;             for (int m = 0; m < 4; ++m) { const size_t off = (size_t)(row0 + ai * HALF + m * 16) * ldc + col0;
; #pragma unroll
;                 for (int bj = 0; bj < 2; ++bj)
; #pragma unroll
;                     for (int n = 0; n < 2; ++n) *(f32x4*)(out + off + bj * HALF + n * 16) = res[m][bj][n] + acc[ai][bj][m][n]; }
;             asm volatile("" ::: "memory");
;         }
;     }
.LBB0_461:
	s_cmp_eq_u32 s101, 1
	s_cbranch_scc1 .Lp3_epi_first
	v_lshl_add_u32 v200, s24, 8, v146
	v_lshl_or_b32 v140, s45, 8, v148
	v_ashrrev_i32_e32 v201, 31, v200
	v_ashrrev_i32_e32 v141, 31, v140
	v_readlane_b32 s48, v254, 0
	v_lshlrev_b64 v[144:145], 13, v[200:201]
	v_or_b32_e32 v168, 16, v200
	v_or_b32_e32 v184, 32, v200
	v_or_b32_e32 v200, 48, v200
	v_lshlrev_b64 v[140:141], 2, v[140:141]
	v_readlane_b32 s49, v254, 1
	v_ashrrev_i32_e32 v169, 31, v168
	v_ashrrev_i32_e32 v185, 31, v184
	v_ashrrev_i32_e32 v201, 31, v200
	v_lshl_add_u64 v[142:143], s[48:49], 0, v[140:141]
	v_lshlrev_b64 v[216:217], 13, v[168:169]
	v_lshlrev_b64 v[218:219], 13, v[184:185]
	v_lshlrev_b64 v[220:221], 13, v[200:201]
	v_lshl_add_u64 v[164:165], v[142:143], 0, v[144:145]
	v_lshl_add_u64 v[180:181], v[142:143], 0, v[216:217]
	v_lshl_add_u64 v[196:197], v[142:143], 0, v[218:219]
	v_lshl_add_u64 v[212:213], v[142:143], 0, v[220:221]
	global_load_dwordx4 v[152:155], v[164:165], off
	global_load_dwordx4 v[156:159], v[164:165], off offset:64
	global_load_dwordx4 v[160:163], v[164:165], off offset:512
	s_nop 0
	global_load_dwordx4 v[164:167], v[164:165], off offset:576
	s_nop 0
	global_load_dwordx4 v[168:171], v[180:181], off
	global_load_dwordx4 v[172:175], v[180:181], off offset:64
	global_load_dwordx4 v[176:179], v[180:181], off offset:512
	s_nop 0
	global_load_dwordx4 v[180:183], v[180:181], off offset:576
	s_nop 0
	global_load_dwordx4 v[184:187], v[196:197], off
	global_load_dwordx4 v[188:191], v[196:197], off offset:64
	global_load_dwordx4 v[192:195], v[196:197], off offset:512
	s_nop 0
	global_load_dwordx4 v[196:199], v[196:197], off offset:576
	s_nop 0
	global_load_dwordx4 v[200:203], v[212:213], off
	global_load_dwordx4 v[204:207], v[212:213], off offset:64
	global_load_dwordx4 v[208:211], v[212:213], off offset:512
	s_nop 0
	global_load_dwordx4 v[212:215], v[212:213], off offset:576
	v_lshl_add_u64 v[222:223], s[70:71], 0, v[144:145]
	v_lshl_add_u64 v[220:221], s[70:71], 0, v[220:221]
	v_lshl_add_u64 v[222:223], v[222:223], 0, v[140:141]
	v_lshl_add_u64 v[216:217], s[70:71], 0, v[216:217]
	v_lshl_add_u64 v[218:219], s[70:71], 0, v[218:219]
	v_lshl_add_u64 v[220:221], v[220:221], 0, v[140:141]
	v_lshl_add_u64 v[216:217], v[216:217], 0, v[140:141]
	v_lshl_add_u64 v[218:219], v[218:219], 0, v[140:141]
	s_andn2_b64 vcc, exec, s[0:1]
	s_mov_b64 s[0:1], -1
	v_readlane_b32 s50, v254, 2
	v_readlane_b32 s51, v254, 3
	v_readlane_b32 s52, v254, 4
	v_readlane_b32 s53, v254, 5
	v_readlane_b32 s54, v254, 6
	v_readlane_b32 s55, v254, 7
	v_readlane_b32 s56, v254, 8
	v_readlane_b32 s57, v254, 9
	v_readlane_b32 s58, v254, 10
	v_readlane_b32 s59, v254, 11
	v_readlane_b32 s60, v254, 12
	v_readlane_b32 s61, v254, 13
	v_readlane_b32 s62, v254, 14
	v_readlane_b32 s63, v254, 15
	s_waitcnt vmcnt(0)
	v_pk_add_f32 v[126:127], v[126:127], v[154:155]
	v_pk_add_f32 v[124:125], v[124:125], v[152:153]
	v_pk_add_f32 v[122:123], v[122:123], v[158:159]
	v_pk_add_f32 v[120:121], v[120:121], v[156:157]
	v_pk_add_f32 v[106:107], v[106:107], v[162:163]
	v_pk_add_f32 v[70:71], v[70:71], v[210:211]
	v_pk_add_f32 v[68:69], v[68:69], v[208:209]
	v_pk_add_f32 v[66:67], v[66:67], v[214:215]
	v_pk_add_f32 v[64:65], v[64:65], v[212:213]
	v_pk_add_f32 v[104:105], v[104:105], v[160:161]
	v_pk_add_f32 v[98:99], v[98:99], v[166:167]
	v_pk_add_f32 v[96:97], v[96:97], v[164:165]
	v_pk_add_f32 v[118:119], v[118:119], v[170:171]
	v_pk_add_f32 v[116:117], v[116:117], v[168:169]
	v_pk_add_f32 v[114:115], v[114:115], v[174:175]
	v_pk_add_f32 v[112:113], v[112:113], v[172:173]
	v_pk_add_f32 v[90:91], v[90:91], v[178:179]
	v_pk_add_f32 v[88:89], v[88:89], v[176:177]
	v_pk_add_f32 v[86:87], v[86:87], v[182:183]
	v_pk_add_f32 v[84:85], v[84:85], v[180:181]
	v_pk_add_f32 v[110:111], v[110:111], v[186:187]
	v_pk_add_f32 v[108:109], v[108:109], v[184:185]
	v_pk_add_f32 v[102:103], v[102:103], v[190:191]
	v_pk_add_f32 v[100:101], v[100:101], v[188:189]
	v_pk_add_f32 v[78:79], v[78:79], v[194:195]
	v_pk_add_f32 v[76:77], v[76:77], v[192:193]
	v_pk_add_f32 v[74:75], v[74:75], v[198:199]
	v_pk_add_f32 v[72:73], v[72:73], v[196:197]
	v_pk_add_f32 v[94:95], v[94:95], v[202:203]
	v_pk_add_f32 v[92:93], v[92:93], v[200:201]
	v_pk_add_f32 v[82:83], v[82:83], v[206:207]
	v_pk_add_f32 v[80:81], v[80:81], v[204:205]
	global_store_dwordx4 v[222:223], v[124:127], off
	global_store_dwordx4 v[222:223], v[120:123], off offset:64
	global_store_dwordx4 v[222:223], v[104:107], off offset:512
	global_store_dwordx4 v[222:223], v[96:99], off offset:576
	global_store_dwordx4 v[216:217], v[116:119], off
	global_store_dwordx4 v[216:217], v[112:115], off offset:64
	global_store_dwordx4 v[216:217], v[88:91], off offset:512
	global_store_dwordx4 v[216:217], v[84:87], off offset:576
	global_store_dwordx4 v[218:219], v[108:111], off
	global_store_dwordx4 v[218:219], v[100:103], off offset:64
	global_store_dwordx4 v[218:219], v[76:79], off offset:512
	global_store_dwordx4 v[218:219], v[72:75], off offset:576
	global_store_dwordx4 v[220:221], v[92:95], off
	global_store_dwordx4 v[220:221], v[80:83], off offset:64
	global_store_dwordx4 v[220:221], v[68:71], off offset:512
	global_store_dwordx4 v[220:221], v[64:67], off offset:576
	v_lshl_add_u64 v[152:153], v[144:145], 0, s[8:9]
	v_lshl_add_u64 v[154:155], v[144:145], 0, s[10:11]
	v_lshl_add_u64 v[156:157], v[144:145], 0, s[12:13]
	v_lshl_add_u64 v[144:145], v[144:145], 0, s[14:15]
	v_lshl_add_u64 v[80:81], v[142:143], 0, v[152:153]
	v_lshl_add_u64 v[96:97], v[142:143], 0, v[154:155]
	v_lshl_add_u64 v[108:109], v[142:143], 0, v[156:157]
	v_lshl_add_u64 v[124:125], v[142:143], 0, v[144:145]
	global_load_dwordx4 v[64:67], v[80:81], off
	global_load_dwordx4 v[68:71], v[80:81], off offset:64
	global_load_dwordx4 v[72:75], v[80:81], off offset:512
	global_load_dwordx4 v[76:79], v[80:81], off offset:576
	s_nop 0
	global_load_dwordx4 v[80:83], v[96:97], off
	global_load_dwordx4 v[84:87], v[96:97], off offset:64
	global_load_dwordx4 v[88:91], v[96:97], off offset:512
	global_load_dwordx4 v[92:95], v[96:97], off offset:576
	s_nop 0
	global_load_dwordx4 v[96:99], v[108:109], off
	global_load_dwordx4 v[100:103], v[108:109], off offset:64
	global_load_dwordx4 v[104:107], v[108:109], off offset:512
	s_nop 0
	global_load_dwordx4 v[108:111], v[108:109], off offset:576
	s_nop 0
	global_load_dwordx4 v[112:115], v[124:125], off
	global_load_dwordx4 v[116:119], v[124:125], off offset:64
	global_load_dwordx4 v[120:123], v[124:125], off offset:512
	s_nop 0
	global_load_dwordx4 v[124:127], v[124:125], off offset:576
	v_lshl_add_u64 v[142:143], s[70:71], 0, v[152:153]
	v_lshl_add_u64 v[152:153], s[70:71], 0, v[154:155]
	v_lshl_add_u64 v[154:155], s[70:71], 0, v[156:157]
	v_lshl_add_u64 v[144:145], s[70:71], 0, v[144:145]
	v_lshl_add_u64 v[142:143], v[142:143], 0, v[140:141]
	v_lshl_add_u64 v[152:153], v[152:153], 0, v[140:141]
	v_lshl_add_u64 v[154:155], v[154:155], 0, v[140:141]
	v_lshl_add_u64 v[140:141], v[144:145], 0, v[140:141]
	s_waitcnt vmcnt(15)
; #define PG8_BAR __builtin_amdgcn_s_barrier()
;     __device__ __forceinline__ void operator()(const f32x4 (&acc)[2][2][4][2], const Unit& u, int wr, int wc, int fr, int fq) const {
;         const int row0 = u.pm * BM + wr * 64 + fr, col0 = u.pn * BM + wc * 32 + 4 * fq;
; #pragma unroll
;         for (int ai = 0; ai < 2; ++ai) {
;             f32x4 res[4][2][2];
; #pragma unroll
;             for (int m = 0; m < 4; ++m) { const size_t off = (size_t)(row0 + ai * HALF + m * 16) * ldc + col0;
; #pragma unroll
;                 for (int bj = 0; bj < 2; ++bj)
; #pragma unroll
;                     for (int n = 0; n < 2; ++n) res[m][bj][n] = *(const f32x4*)(base + off + bj * HALF + n * 16); }
;             asm volatile("" ::: "memory");
; #pragma unroll
;             for (int m = 0; m < 4; ++m) { const size_t off = (size_t)(row0 + ai * HALF + m * 16) * ldc + col0;
; #pragma unroll
;                 for (int bj = 0; bj < 2; ++bj)
; #pragma unroll
;                     for (int n = 0; n < 2; ++n) *(f32x4*)(out + off + bj * HALF + n * 16) = res[m][bj][n] + acc[ai][bj][m][n]; }
;             asm volatile("" ::: "memory");
;         }
;     }
; template <class Epi, class Sched, bool ALIGN_EPI = false, bool SP2 = false>
; __device__ __forceinline__ void gemm_phase(PG8_LAS unsigned char* lds, const Gemm g, const Sched& S, const Epi& E) {
;     ...
;         if constexpr (ALIGN_EPI) { if (wr == 0) PG8_BAR; }
;         if constexpr (!Epi::AFTER_DRAIN) { E(acc, cur, wr, wc, fr, fq); S.done(cur); }
;         if (!has_next) break;
; #pragma unroll
;         for (int a = 0; a < 2; ++a)
; #pragma unroll
;             for (int b = 0; b < 2; ++b)
; #pragma unroll
;                 for (int m = 0; m < 4; ++m)
; #pragma unroll
;                     for (int n = 0; n < 2; ++n) acc[a][b][m][n] = (f32x4){0.f, 0.f, 0.f, 0.f};
;         cur = nxt; cA = nA; cB = nB; ++ui;
;         if constexpr (ALIGN_EPI) { if (wr == 1) PG8_BAR; }
;     }
	v_pk_add_f32 v[62:63], v[62:63], v[66:67]
	v_pk_add_f32 v[60:61], v[60:61], v[64:65]
	s_waitcnt vmcnt(14)
	v_pk_add_f32 v[58:59], v[58:59], v[70:71]
	v_pk_add_f32 v[56:57], v[56:57], v[68:69]
	s_waitcnt vmcnt(13)
	v_pk_add_f32 v[42:43], v[42:43], v[74:75]
	s_waitcnt vmcnt(1)
	v_pk_add_f32 v[6:7], v[6:7], v[122:123]
	v_pk_add_f32 v[4:5], v[4:5], v[120:121]
	s_waitcnt vmcnt(0)
	v_pk_add_f32 v[2:3], v[2:3], v[126:127]
	v_pk_add_f32 v[0:1], v[0:1], v[124:125]
	v_pk_add_f32 v[40:41], v[40:41], v[72:73]
	v_pk_add_f32 v[34:35], v[34:35], v[78:79]
	v_pk_add_f32 v[32:33], v[32:33], v[76:77]
	v_pk_add_f32 v[54:55], v[54:55], v[82:83]
	v_pk_add_f32 v[52:53], v[52:53], v[80:81]
	v_pk_add_f32 v[50:51], v[50:51], v[86:87]
	v_pk_add_f32 v[48:49], v[48:49], v[84:85]
	v_pk_add_f32 v[26:27], v[26:27], v[90:91]
	v_pk_add_f32 v[24:25], v[24:25], v[88:89]
	v_pk_add_f32 v[22:23], v[22:23], v[94:95]
	v_pk_add_f32 v[20:21], v[20:21], v[92:93]
	v_pk_add_f32 v[46:47], v[46:47], v[98:99]
	v_pk_add_f32 v[44:45], v[44:45], v[96:97]
	v_pk_add_f32 v[38:39], v[38:39], v[102:103]
	v_pk_add_f32 v[36:37], v[36:37], v[100:101]
	v_pk_add_f32 v[14:15], v[14:15], v[106:107]
	v_pk_add_f32 v[12:13], v[12:13], v[104:105]
	v_pk_add_f32 v[10:11], v[10:11], v[110:111]
	v_pk_add_f32 v[8:9], v[8:9], v[108:109]
	v_pk_add_f32 v[30:31], v[30:31], v[114:115]
	v_pk_add_f32 v[28:29], v[28:29], v[112:113]
	v_pk_add_f32 v[18:19], v[18:19], v[118:119]
	v_pk_add_f32 v[16:17], v[16:17], v[116:117]
	global_store_dwordx4 v[142:143], v[60:63], off
	global_store_dwordx4 v[142:143], v[56:59], off offset:64
	global_store_dwordx4 v[142:143], v[40:43], off offset:512
	global_store_dwordx4 v[142:143], v[32:35], off offset:576
	global_store_dwordx4 v[152:153], v[52:55], off
	global_store_dwordx4 v[152:153], v[48:51], off offset:64
	global_store_dwordx4 v[152:153], v[24:27], off offset:512
	global_store_dwordx4 v[152:153], v[20:23], off offset:576
	global_store_dwordx4 v[154:155], v[44:47], off
	global_store_dwordx4 v[154:155], v[36:39], off offset:64
	global_store_dwordx4 v[154:155], v[12:15], off offset:512
	global_store_dwordx4 v[154:155], v[8:11], off offset:576
	global_store_dwordx4 v[140:141], v[28:31], off
	global_store_dwordx4 v[140:141], v[16:19], off offset:64
	global_store_dwordx4 v[140:141], v[4:7], off offset:512
	global_store_dwordx4 v[140:141], v[0:3], off offset:576
.Lp3_epi_tail:
	s_cbranch_vccnz .LBB0_450
	s_andn2_b64 vcc, exec, s[2:3]
	s_cbranch_vccnz .LBB0_449
	s_barrier
	s_branch .LBB0_449
.Lp3_preloaded:
	v_mov_b32_e32 v8, v236
	v_mov_b32_e32 v9, v237
	v_mov_b32_e32 v10, v238
	v_mov_b32_e32 v11, v239
	v_mov_b32_e32 v4, v240
	v_mov_b32_e32 v5, v241
	v_mov_b32_e32 v6, v242
	v_mov_b32_e32 v7, v243
	v_mov_b32_e32 v0, v244
	v_mov_b32_e32 v1, v245
	v_mov_b32_e32 v2, v246
	v_mov_b32_e32 v3, v247
	s_branch .LBB0_458
.Lp3_epi_first:
	s_mov_b32 s101, 0
	global_store_dwordx4 v250, v[124:127], s[70:71]
	global_store_dwordx4 v250, v[120:123], s[70:71] offset:64
	global_store_dwordx4 v250, v[104:107], s[70:71] offset:512
	global_store_dwordx4 v250, v[96:99], s[70:71] offset:576
	s_add_u32 s88, s70, 0x20000
	s_addc_u32 s89, s71, 0
	s_nop 0
	global_store_dwordx4 v250, v[116:119], s[88:89]
	global_store_dwordx4 v250, v[112:115], s[88:89] offset:64
	global_store_dwordx4 v250, v[88:91], s[88:89] offset:512
	global_store_dwordx4 v250, v[84:87], s[88:89] offset:576
	s_add_u32 s90, s70, 0x40000
	s_addc_u32 s91, s71, 0
	s_nop 0
	global_store_dwordx4 v250, v[108:111], s[90:91]
	global_store_dwordx4 v250, v[100:103], s[90:91] offset:64
	global_store_dwordx4 v250, v[76:79], s[90:91] offset:512
	global_store_dwordx4 v250, v[72:75], s[90:91] offset:576
	s_add_u32 s92, s70, 0x60000
	s_addc_u32 s93, s71, 0
	s_nop 0
	global_store_dwordx4 v250, v[92:95], s[92:93]
	global_store_dwordx4 v250, v[80:83], s[92:93] offset:64
	global_store_dwordx4 v250, v[68:71], s[92:93] offset:512
	global_store_dwordx4 v250, v[64:67], s[92:93] offset:576
	s_add_u32 s94, s70, 0x100000
	s_addc_u32 s95, s71, 0
	s_nop 0
	global_store_dwordx4 v250, v[60:63], s[94:95]
	global_store_dwordx4 v250, v[56:59], s[94:95] offset:64
	global_store_dwordx4 v250, v[40:43], s[94:95] offset:512
	global_store_dwordx4 v250, v[32:35], s[94:95] offset:576
	s_add_u32 s96, s70, 0x120000
	s_addc_u32 s97, s71, 0
	s_nop 0
	global_store_dwordx4 v250, v[52:55], s[96:97]
	global_store_dwordx4 v250, v[48:51], s[96:97] offset:64
	global_store_dwordx4 v250, v[24:27], s[96:97] offset:512
	global_store_dwordx4 v250, v[20:23], s[96:97] offset:576
	s_add_u32 s98, s70, 0x140000
	s_addc_u32 s99, s71, 0
	s_nop 0
	global_store_dwordx4 v250, v[44:47], s[98:99]
	global_store_dwordx4 v250, v[36:39], s[98:99] offset:64
	global_store_dwordx4 v250, v[12:15], s[98:99] offset:512
	global_store_dwordx4 v250, v[8:11], s[98:99] offset:576
	s_add_u32 s88, s70, 0x160000
	s_addc_u32 s89, s71, 0
	s_nop 0
	global_store_dwordx4 v250, v[28:31], s[88:89]
	global_store_dwordx4 v250, v[16:19], s[88:89] offset:64
	global_store_dwordx4 v250, v[4:7], s[88:89] offset:512
	global_store_dwordx4 v250, v[0:3], s[88:89] offset:576
	v_readlane_b32 s48, v254, 0
	v_readlane_b32 s49, v254, 1
	s_andn2_b64 vcc, exec, s[0:1]
	s_mov_b64 s[0:1], -1
	v_readlane_b32 s50, v254, 2
	v_readlane_b32 s51, v254, 3
	v_readlane_b32 s52, v254, 4
	v_readlane_b32 s53, v254, 5
	v_readlane_b32 s54, v254, 6
	v_readlane_b32 s55, v254, 7
	v_readlane_b32 s56, v254, 8
	v_readlane_b32 s57, v254, 9
	v_readlane_b32 s58, v254, 10
	v_readlane_b32 s59, v254, 11
	v_readlane_b32 s60, v254, 12
	v_readlane_b32 s61, v254, 13
	v_readlane_b32 s62, v254, 14
	v_readlane_b32 s63, v254, 15
	s_branch .Lp3_epi_tail
